# attention code shifted by 4 bytes (loop head at 4 mod 8): placement test
# speedup vs baseline: 1.0060x; 1.0060x over previous
; __global__ void __launch_bounds__(NTHR, 2) mk_fwd(Args a_by_value) {
;     ...
;         } else if (PH_EN(5) && k == 5) {
;             const int vcu = (G % 8 == 0) ? (bid % 8) * (G / 8) + bid / 8 : bid;
;             for (int rep = 0; rep < REP_ATT; ++rep) for (int unit = vcu; unit < 512; unit += G) attn_unit(a, layer, (unit & 255) * 2 + (unit >> 8), lds);
;             for (int rep5 = 0; rep5 < REP_CMB; ++rep5) ssd_combine_rows(a, G);
.LBB0_60:
	s_cmp_gt_i32 s9, 4
	s_mov_b64 s[2:3], -1
	s_cbranch_scc0 .LBB0_91
	s_bfe_u32 s2, s36, 0x10003
	s_nop 1
	v_writelane_b32 v255, s2, 42
	s_cmp_eq_u32 s2, 1
	s_cbranch_scc1 .LBB0_83
	s_nop 0

; __device__ __forceinline__ void attn_unit(CArgs a, int layer, int unit, LAS unsigned char* lds) {
;     ...
;     lrun += __shfl_xor(lrun, 32);
;     if (hi == 0) wsf[32 + r32] = 1.f / lrun;
.LBB0_81:
	ds_bpermute_b32 v35, v164, v172
	v_and_b32_e32 v34, 0x3fffffc0, v159
	v_lshl_add_u32 v34, v34, 2, 0
	v_cmp_gt_u32_e32 vcc, 32, v0
	s_and_saveexec_b64 s[2:3], vcc
	s_cbranch_execz .LBB0_65
	s_waitcnt lgkmcnt(0)
	v_add_f32_e32 v35, v172, v35
	v_div_scale_f32 v36, s[12:13], v35, v35, 1.0
	v_rcp_f32_e32 v37, v36
	v_div_scale_f32 v38, vcc, 1.0, v35, 1.0
	v_fma_f32 v39, -v36, v37, 1.0
	v_fmac_f32_e32 v37, v39, v37
	v_mul_f32_e32 v39, v38, v37
	v_fma_f32 v40, -v36, v39, v38
	v_fmac_f32_e32 v39, v40, v37
	v_fma_f32 v36, -v36, v39, v38
	v_div_fmas_f32 v36, v36, v37, v39
	v_div_fixup_f32 v35, v36, v35, 1.0
	v_lshl_add_u32 v36, v161, 2, v34
	ds_write_b32 v36, v35 offset:45184
	s_branch .LBB0_65
	s_nop 0
